# R1 staging: second 32-row round K/cos/sin loads issued up front with the first round into free registers, copied at the original load positions
# baseline (speedup 1.0000x reference)
; #define LAS __attribute__((address_space(3)))
; __device__ __forceinline__ void unpack8(const u32x4 w, float* f) { f[0] = bf_lo(w.x); f[1] = bf_hi(w.x); f[2] = bf_lo(w.y); f[3] = bf_hi(w.y); f[4] = bf_lo(w.z); f[5] = bf_hi(w.z); f[6] = bf_lo(w.w); f[7] = bf_hi(w.w); }
; __device__ __forceinline__ int otid() { int t = threadIdx.x; asm volatile("" : "+v"(t)); return t; }
; __device__ __forceinline__ void r1_item(const bf16_t* __restrict__ projT, bf16_t* stloc, const float* __restrict__ cosT, const float* __restrict__ sinT, float lgf2, float lgb2, int item, int seqlen, LAS unsigned char* lds) {
;     const int tid = otid(), w = __builtin_amdgcn_readfirstlane(tid >> 6), lane = tid & 63, c = lane & 31, hh = lane >> 5;
;     const int ch = item >> 2, h = item & 3, tok0 = ch * 128, pos0 = tok0 % seqlen;
;     LAS bf16_t* KTf = (LAS bf16_t*)lds; LAS bf16_t* KTb = (LAS bf16_t*)(lds + 128 * KT_STRIDE * 2);
;     const float scale = 0.08838834764831845f;
;     bf16x8 af[8];
;     { const bf16_t* vp = projT + (size_t)(1024 + h * 256 + 32 * w + c) * MG + tok0 + 8 * hh;
; #pragma unroll
;       for (int s = 0; s < 8; ++s) af[s] = *(const bf16x8*)(vp + 16 * s); }
; #pragma unroll
;     for (int it = 0; it < 2; ++it) {
;         const int id = tid + NTHREADS * it, d = id >> 4, t8 = id & 15;
;         float k1[8], k2[8];
;         unpack8(__builtin_nontemporal_load((const u32x4*)(projT + (size_t)(512 + h * 128 + d) * MG + tok0 + 8 * t8)), k1);
;         unpack8(__builtin_nontemporal_load((const u32x4*)(projT + (size_t)(512 + h * 128 + d + 64) * MG + tok0 + 8 * t8)), k2);
;         const f32x4 c0 = *(const f32x4*)(cosT + (size_t)d * 16384 + pos0 + 8 * t8), c1 = *(const f32x4*)(cosT + (size_t)d * 16384 + pos0 + 8 * t8 + 4);
;         const f32x4 s0 = *(const f32x4*)(sinT + (size_t)d * 16384 + pos0 + 8 * t8), s1 = *(const f32x4*)(sinT + (size_t)d * 16384 + pos0 + 8 * t8 + 4);
.LBB0_361:
	s_mov_b64 s[6:7], 0
	s_add_u32 s10, s30, s6
	s_addc_u32 s11, s31, s7
	s_and_b32 s6, s27, 6
	s_or_b32 s58, s6, s76
	s_lshl_b64 s[6:7], s[58:59], 2
	s_add_u32 s6, s10, s6
	s_addc_u32 s7, s11, s7
	global_load_dwordx2 v[66:67], v244, s[6:7]
	s_mov_b64 s[6:7], 0
	s_add_u32 s6, s30, s6
	s_addc_u32 s7, s31, s7
	s_add_u32 s40, s6, 0x18240000
	s_addc_u32 s41, s7, 0
	s_mov_b64 s[6:7], 0
	s_mov_b64 s[10:11], 0
	s_add_u32 s17, s30, s10
	s_addc_u32 s34, s31, s11
	s_mov_b64 s[28:29], 0
	s_add_u32 s11, s30, s28
	v_mov_b32_e32 v70, v232
	s_addc_u32 s16, s31, s29
	s_and_b32 s28, s25, 0xffffff80
	v_readfirstlane_b32 s10, v70
	s_ashr_i32 s43, s10, 1
	s_ashr_i32 s29, s28, 31
	s_ashr_i32 s10, s25, 31
	s_lshl_b64 s[38:39], s[28:29], 1
	s_add_i32 s28, s28, s10
	s_xor_b32 s28, s28, s10
	s_mul_hi_u32 s29, s28, s67
	s_mul_i32 s29, s29, s71
	s_sub_i32 s28, s28, s29
	s_and_b32 s33, s42, 3
	s_andn2_b32 s43, s43, 31
	s_sub_i32 s29, s28, s71
	s_cmp_ge_u32 s28, s71
	s_cselect_b32 s28, s29, s28
	v_and_b32_e32 v118, 31, v70
	s_sub_i32 s29, s28, s71
	v_lshl_or_b32 v0, s33, 8, v118
	s_cmp_ge_u32 s28, s71
	v_add_u32_e32 v0, s43, v0
	s_cselect_b32 s28, s29, s28
	v_add_u32_e32 v2, 0x400, v0
	s_xor_b32 s28, s28, s10
	v_ashrrev_i32_e32 v3, 31, v2
	s_sub_i32 s28, s28, s10
	s_lshl_b32 s10, s33, 7
	v_lshlrev_b64 v[2:3], 15, v[2:3]
	s_bitset1_b32 s10, 9
	v_bfe_u32 v51, v70, 5, 1
	v_lshl_add_u64 v[2:3], s[40:41], 0, v[2:3]
	s_add_u32 s40, s40, s38
	v_lshl_add_u64 v[2:3], v[2:3], 0, s[38:39]
	v_lshlrev_b32_e32 v0, 4, v51
	s_addc_u32 s41, s41, s39
	v_lshlrev_b32_e32 v71, 3, v70
	s_ashr_i32 s29, s28, 31
	v_lshl_add_u64 v[2:3], v[2:3], 0, v[0:1]
	v_and_b32_e32 v72, 0x78, v71
	s_lshl_b64 s[28:29], s[28:29], 2
	global_load_dwordx4 v[46:49], v[2:3], off
	global_load_dwordx4 v[42:45], v[2:3], off offset:32
	global_load_dwordx4 v[38:41], v[2:3], off offset:64
	global_load_dwordx4 v[34:37], v[2:3], off offset:96
	global_load_dwordx4 v[30:33], v[2:3], off offset:128
	global_load_dwordx4 v[26:29], v[2:3], off offset:160
	global_load_dwordx4 v[22:25], v[2:3], off offset:192
	global_load_dwordx4 v[18:21], v[2:3], off offset:224
	v_lshlrev_b32_e32 v2, 1, v72
	v_mov_b32_e32 v3, v1
	s_add_u32 s38, s17, s28
	v_ashrrev_i32_e32 v68, 4, v70
	v_lshl_add_u64 v[56:57], s[40:41], 0, v[2:3]
	s_addc_u32 s39, s34, s29
	v_add_u32_e32 v50, 0, v2
	v_add_u32_e32 v2, s10, v68
	s_add_u32 s28, s11, s28
	v_ashrrev_i32_e32 v3, 31, v2
	v_lshlrev_b32_e32 v4, 2, v72
	v_mov_b32_e32 v5, v1
	s_addc_u32 s29, s16, s29
	v_lshlrev_b64 v[2:3], 15, v[2:3]
	v_lshl_add_u64 v[6:7], s[38:39], 0, v[4:5]
	s_mov_b64 s[38:39], 0xc40000
	v_lshl_add_u64 v[4:5], s[28:29], 0, v[4:5]
	s_mov_b64 s[16:17], 0x1040000
	v_lshl_add_u64 v[2:3], v[56:57], 0, v[2:3]
	v_ashrrev_i32_e32 v69, 31, v68
	v_lshl_add_u64 v[52:53], v[6:7], 0, s[38:39]
	v_lshl_add_u64 v[54:55], v[4:5], 0, s[16:17]
	global_load_dwordx4 v[6:9], v[2:3], off nt
	v_add_co_u32_e32 v2, vcc, s13, v2
	v_lshlrev_b64 v[14:15], 16, v[68:69]
	s_nop 0
	v_addc_co_u32_e32 v3, vcc, 0, v3, vcc
	v_lshl_add_u64 v[16:17], v[52:53], 0, v[14:15]
	v_lshl_add_u64 v[58:59], v[54:55], 0, v[14:15]
	global_load_dwordx4 v[10:13], v[2:3], off nt
	s_nop 0
	global_load_dwordx4 v[2:5], v[16:17], off offset:16
	global_load_dwordx4 v[74:77], v[16:17], off
	s_nop 0
	global_load_dwordx4 v[14:17], v[58:59], off offset:16
	global_load_dwordx4 v[78:81], v[58:59], off
	v_add_u32_e32 v190, 0x200, v70
	v_ashrrev_i32_e32 v192, 4, v190
	v_add_u32_e32 v190, s10, v192
	v_ashrrev_i32_e32 v191, 31, v190
	v_lshlrev_b64 v[190:191], 15, v[190:191]
	v_lshl_add_u64 v[190:191], v[56:57], 0, v[190:191]
	global_load_dwordx4 v[196:199], v[190:191], off nt
	v_add_co_u32_e32 v190, vcc, s13, v190
	v_ashrrev_i32_e32 v193, 31, v192
	s_nop 0
	v_addc_co_u32_e32 v191, vcc, 0, v191, vcc
	global_load_dwordx4 v[200:203], v[190:191], off nt
	v_lshlrev_b64 v[190:191], 16, v[192:193]
	v_lshl_add_u64 v[194:195], v[52:53], 0, v[190:191]
	v_lshl_add_u64 v[190:191], v[54:55], 0, v[190:191]
	global_load_dwordx4 v[204:207], v[194:195], off offset:16
	global_load_dwordx4 v[208:211], v[194:195], off
	global_load_dwordx4 v[212:215], v[190:191], off offset:16
	global_load_dwordx4 v[216:219], v[190:191], off
	s_movk_i32 s11, 0x7f
	v_bitop3_b32 v58, v71, s11, v242 bitop3:0x6c
	v_cvt_f32_ubyte0_e32 v58, v58
	s_movk_i32 s11, 0x7e
	s_waitcnt vmcnt(20)
	v_mul_f32_e32 v58, v66, v58
	v_or_b32_e32 v59, 1, v72
	v_bitop3_b32 v61, v71, s11, v242 bitop3:0x6c
	v_exp_f32_e32 v60, v58
	v_cvt_f32_ubyte0_e32 v58, v72
	v_cvt_f32_ubyte0_e32 v61, v61
	v_cvt_f32_ubyte0_e32 v59, v59
	v_mul_f32_e32 v58, v67, v58
	v_mul_f32_e32 v61, v66, v61
	v_mul_f32_e32 v59, v67, v59
	v_exp_f32_e32 v58, v58
	v_exp_f32_e32 v61, v61
	v_exp_f32_e32 v59, v59
	s_movk_i32 s11, 0x7d
	s_add_u32 s6, s0, s6
	s_addc_u32 s7, s1, s7
	s_add_i32 s42, s42, s52
	s_add_i32 s27, s27, s21
	s_add_i32 s25, s25, s22
	s_waitcnt vmcnt(11)
	v_lshlrev_b32_e32 v62, 16, v6
	v_and_b32_e32 v63, 0xffff0000, v6
	v_or_b32_e32 v6, 2, v72
	v_cvt_f32_ubyte0_e32 v6, v6
	v_mul_f32_e32 v6, v67, v6
	v_lshlrev_b32_e32 v90, 16, v8
	v_and_b32_e32 v91, 0xffff0000, v8
	v_or_b32_e32 v8, 7, v72
	s_waitcnt vmcnt(10)
	v_lshlrev_b32_e32 v64, 16, v10
	v_and_b32_e32 v65, 0xffff0000, v10
	s_waitcnt vmcnt(6)
; #define LAS __attribute__((address_space(3)))
; __device__ __forceinline__ void unpack8(const u32x4 w, float* f) { f[0] = bf_lo(w.x); f[1] = bf_hi(w.x); f[2] = bf_lo(w.y); f[3] = bf_hi(w.y); f[4] = bf_lo(w.z); f[5] = bf_hi(w.z); f[6] = bf_lo(w.w); f[7] = bf_hi(w.w); }
; __device__ __forceinline__ u32x4 pack8(const float* f) { u32x4 w; w.x = cvt_pk_bf16(f[0], f[1]); w.y = cvt_pk_bf16(f[2], f[3]); w.z = cvt_pk_bf16(f[4], f[5]); w.w = cvt_pk_bf16(f[6], f[7]); return w; }
; __device__ __forceinline__ void r1_item(const bf16_t* __restrict__ projT, bf16_t* stloc, const float* __restrict__ cosT, const float* __restrict__ sinT, float lgf2, float lgb2, int item, int seqlen, LAS unsigned char* lds) {
;     ...
;         const int id = tid + NTHREADS * it, d = id >> 4, t8 = id & 15;
;         float k1[8], k2[8];
;         unpack8(__builtin_nontemporal_load((const u32x4*)(projT + (size_t)(512 + h * 128 + d) * MG + tok0 + 8 * t8)), k1);
;         unpack8(__builtin_nontemporal_load((const u32x4*)(projT + (size_t)(512 + h * 128 + d + 64) * MG + tok0 + 8 * t8)), k2);
;         const f32x4 c0 = *(const f32x4*)(cosT + (size_t)d * 16384 + pos0 + 8 * t8), c1 = *(const f32x4*)(cosT + (size_t)d * 16384 + pos0 + 8 * t8 + 4);
;         const f32x4 s0 = *(const f32x4*)(sinT + (size_t)d * 16384 + pos0 + 8 * t8), s1 = *(const f32x4*)(sinT + (size_t)d * 16384 + pos0 + 8 * t8 + 4);
;         float f1[8], f2[8], b1[8], b2[8];
; #pragma unroll
;         for (int j = 0; j < 8; ++j) { const float cv = j < 4 ? c0[j & 3] : c1[j & 3], sv = j < 4 ? s0[j & 3] : s1[j & 3];
;             const float r1 = (k1[j] * cv - k2[j] * sv) * scale, r2 = (k1[j] * sv + k2[j] * cv) * scale;
;             const int tl = 8 * t8 + j; const float df = __builtin_amdgcn_exp2f((float)(127 - tl) * lgf2), db = __builtin_amdgcn_exp2f((float)tl * lgb2);
;             f1[j] = r1 * df; f2[j] = r2 * df; b1[j] = r1 * db; b2[j] = r2 * db; }
;         *(LAS u32x4*)(KTf + d * KT_STRIDE + 8 * t8) = pack8(f1); *(LAS u32x4*)(KTf + (d + 64) * KT_STRIDE + 8 * t8) = pack8(f2);
;         *(LAS u32x4*)(KTb + d * KT_STRIDE + 8 * t8) = pack8(b1); *(LAS u32x4*)(KTb + (d + 64) * KT_STRIDE + 8 * t8) = pack8(b2);
	v_pk_mul_f32 v[82:83], v[78:79], v[62:63]
	v_bitop3_b32 v10, v71, s11, v242 bitop3:0x6c
	v_pk_fma_f32 v[82:83], v[74:75], v[64:65], v[82:83]
	v_pk_mul_f32 v[64:65], v[78:79], v[64:65]
	v_cvt_f32_ubyte0_e32 v10, v10
	v_pk_fma_f32 v[62:63], v[74:75], v[62:63], v[64:65] neg_lo:[0,0,1] neg_hi:[0,0,1]
	v_mul_f32_e32 v10, v66, v10
	v_pk_mul_f32 v[62:63], v[62:63], s[64:65] op_sel_hi:[1,0]
	s_movk_i32 s11, 0x7c
	v_pk_mul_f32 v[74:75], v[60:61], v[62:63]
	v_pk_mul_f32 v[78:79], v[58:59], v[62:63]
	v_exp_f32_e32 v62, v6
	v_or_b32_e32 v6, 3, v72
	v_exp_f32_e32 v64, v10
	v_bitop3_b32 v10, v71, s11, v242 bitop3:0x6c
	v_cvt_f32_ubyte0_e32 v6, v6
	v_cvt_f32_ubyte0_e32 v10, v10
	v_mul_f32_e32 v6, v67, v6
	v_mul_f32_e32 v10, v66, v10
	v_exp_f32_e32 v63, v6
	v_lshlrev_b32_e32 v6, 16, v7
	v_and_b32_e32 v7, 0xffff0000, v7
	v_exp_f32_e32 v65, v10
	v_lshlrev_b32_e32 v10, 16, v11
	v_and_b32_e32 v11, 0xffff0000, v11
	v_pk_mul_f32 v[86:87], v[80:81], v[6:7]
	s_movk_i32 s11, 0x7b
	v_pk_fma_f32 v[86:87], v[76:77], v[10:11], v[86:87]
	v_pk_mul_f32 v[10:11], v[80:81], v[10:11]
	v_lshlrev_b32_e32 v92, 16, v12
	v_pk_fma_f32 v[6:7], v[76:77], v[6:7], v[10:11] neg_lo:[0,0,1] neg_hi:[0,0,1]
	v_or_b32_e32 v11, 5, v72
	v_pk_mul_f32 v[6:7], v[6:7], s[64:65] op_sel_hi:[1,0]
	v_cvt_f32_ubyte0_e32 v11, v11
	v_pk_mul_f32 v[76:77], v[64:65], v[6:7]
	v_pk_mul_f32 v[80:81], v[62:63], v[6:7]
	v_or_b32_e32 v7, 4, v72
	v_cvt_f32_ubyte0_e32 v7, v7
	v_bitop3_b32 v6, v71, s11, v242 bitop3:0x6c
	v_mul_f32_e32 v7, v67, v7
	s_movk_i32 s11, 0x7a
	v_exp_f32_e32 v10, v7
	v_bitop3_b32 v7, v71, s11, v242 bitop3:0x6c
	v_cvt_f32_ubyte0_e32 v6, v6
	v_cvt_f32_ubyte0_e32 v7, v7
	v_mul_f32_e32 v6, v66, v6
	v_mul_f32_e32 v7, v66, v7
	v_mul_f32_e32 v11, v67, v11
	v_exp_f32_e32 v6, v6
	v_exp_f32_e32 v7, v7
	v_exp_f32_e32 v11, v11
	v_and_b32_e32 v93, 0xffff0000, v12
	v_pk_mul_f32 v[94:95], v[14:15], v[90:91]
	v_pk_mul_f32 v[14:15], v[14:15], v[92:93]
	v_pk_fma_f32 v[94:95], v[2:3], v[92:93], v[94:95]
	v_pk_fma_f32 v[2:3], v[2:3], v[90:91], v[14:15] neg_lo:[0,0,1] neg_hi:[0,0,1]
	s_movk_i32 s11, 0x79
	v_pk_mul_f32 v[2:3], v[2:3], s[64:65] op_sel_hi:[1,0]
	v_cvt_f32_ubyte0_e32 v8, v8
	v_pk_mul_f32 v[90:91], v[6:7], v[2:3]
	v_pk_mul_f32 v[92:93], v[10:11], v[2:3]
	v_or_b32_e32 v3, 6, v72
	v_cvt_f32_ubyte0_e32 v3, v3
	v_bitop3_b32 v2, v71, s11, v242 bitop3:0x6c
	v_mul_f32_e32 v3, v67, v3
	s_movk_i32 s11, 0x78
	v_exp_f32_e32 v14, v3
	v_bitop3_b32 v3, v71, s11, v71 bitop3:0xc
	v_cvt_f32_ubyte0_e32 v2, v2
	v_cvt_f32_ubyte0_e32 v3, v3
	v_mul_f32_e32 v8, v67, v8
	v_mul_f32_e32 v2, v66, v2
	v_mul_f32_e32 v3, v66, v3
	v_exp_f32_e32 v15, v8
	v_lshlrev_b32_e32 v8, 16, v9
	v_and_b32_e32 v9, 0xffff0000, v9
	v_exp_f32_e32 v2, v2
	v_exp_f32_e32 v3, v3
	v_lshlrev_b32_e32 v12, 16, v13
	v_and_b32_e32 v13, 0xffff0000, v13
	v_pk_mul_f32 v[66:67], v[16:17], v[8:9]
	v_pk_mul_f32 v[82:83], v[82:83], s[64:65] op_sel_hi:[1,0]
	v_pk_fma_f32 v[66:67], v[4:5], v[12:13], v[66:67]
	v_pk_mul_f32 v[12:13], v[16:17], v[12:13]
	v_pk_mul_f32 v[86:87], v[86:87], s[64:65] op_sel_hi:[1,0]
	v_pk_fma_f32 v[4:5], v[4:5], v[8:9], v[12:13] neg_lo:[0,0,1] neg_hi:[0,0,1]
	v_pk_mul_f32 v[94:95], v[94:95], s[64:65] op_sel_hi:[1,0]
	v_pk_mul_f32 v[66:67], v[66:67], s[64:65] op_sel_hi:[1,0]
	v_pk_mul_f32 v[4:5], v[4:5], s[64:65] op_sel_hi:[1,0]
	v_pk_mul_f32 v[84:85], v[60:61], v[82:83]
	v_pk_mul_f32 v[88:89], v[64:65], v[86:87]
	v_pk_mul_f32 v[96:97], v[6:7], v[94:95]
	v_pk_mul_f32 v[98:99], v[2:3], v[66:67]
	v_pk_mul_f32 v[8:9], v[2:3], v[4:5]
	v_pk_mul_f32 v[4:5], v[14:15], v[4:5]
	v_pk_mul_f32 v[12:13], v[14:15], v[66:67]
	v_cvt_pk_bf16_f32 v72, v74, v75
	v_cvt_pk_bf16_f32 v75, v8, v9
	v_mad_u64_u32 v[8:9], s[16:17], v68, s12, v[50:51]
	v_cvt_pk_bf16_f32 v66, v84, v85
	v_cvt_pk_bf16_f32 v67, v88, v89
	v_cvt_pk_bf16_f32 v68, v96, v97
	v_cvt_pk_bf16_f32 v69, v98, v99
	v_pk_mul_f32 v[82:83], v[58:59], v[82:83]
	v_pk_mul_f32 v[86:87], v[62:63], v[86:87]
	v_pk_mul_f32 v[94:95], v[10:11], v[94:95]
	ds_write_b128 v8, v[66:69] offset:17408
	v_cvt_pk_bf16_f32 v66, v78, v79
	v_cvt_pk_bf16_f32 v67, v80, v81
	v_cvt_pk_bf16_f32 v68, v92, v93
	v_cvt_pk_bf16_f32 v69, v4, v5
	v_cvt_pk_bf16_f32 v73, v76, v77
	v_cvt_pk_bf16_f32 v74, v90, v91
	ds_write_b128 v8, v[66:69] offset:34816
	v_cvt_pk_bf16_f32 v66, v82, v83
	v_cvt_pk_bf16_f32 v67, v86, v87
	v_cvt_pk_bf16_f32 v68, v94, v95
	v_cvt_pk_bf16_f32 v69, v12, v13
	v_add_u32_e32 v4, 0x200, v70
	ds_write_b128 v8, v[72:75]
	ds_write_b128 v8, v[66:69] offset:52224
	v_ashrrev_i32_e32 v8, 4, v4
	v_add_u32_e32 v4, s10, v8
	v_ashrrev_i32_e32 v5, 31, v4
	v_lshlrev_b64 v[4:5], 15, v[4:5]
	v_lshl_add_u64 v[4:5], v[56:57], 0, v[4:5]
	s_waitcnt vmcnt(0)
	v_mov_b64 v[66:67], v[196:197]
	v_mov_b64 v[68:69], v[198:199]
	v_add_co_u32_e32 v4, vcc, s13, v4
	v_ashrrev_i32_e32 v9, 31, v8
	s_nop 0
	v_addc_co_u32_e32 v5, vcc, 0, v5, vcc
	v_mov_b64 v[70:71], v[200:201]
	v_mov_b64 v[72:73], v[202:203]
	v_lshlrev_b64 v[4:5], 16, v[8:9]
	v_lshl_add_u64 v[12:13], v[52:53], 0, v[4:5]
	v_lshl_add_u64 v[4:5], v[54:55], 0, v[4:5]
	v_mov_b64 v[74:75], v[204:205]
	v_mov_b64 v[76:77], v[206:207]
	v_mov_b64 v[78:79], v[208:209]
	v_mov_b64 v[80:81], v[210:211]
	v_mov_b64 v[52:53], v[212:213]
	v_mov_b64 v[54:55], v[214:215]
	v_mov_b64 v[82:83], v[216:217]
	v_mov_b64 v[84:85], v[218:219]
	s_waitcnt vmcnt(5)
	v_lshlrev_b32_e32 v12, 16, v66
	v_and_b32_e32 v13, 0xffff0000, v66
	v_lshlrev_b32_e32 v66, 16, v67
	v_and_b32_e32 v67, 0xffff0000, v67
	s_waitcnt vmcnt(4)
	v_lshlrev_b32_e32 v4, 16, v70
	v_and_b32_e32 v5, 0xffff0000, v70
	s_waitcnt vmcnt(0)
; #define LAS __attribute__((address_space(3)))
; __device__ __forceinline__ u32x4 pack8(const float* f) { u32x4 w; w.x = cvt_pk_bf16(f[0], f[1]); w.y = cvt_pk_bf16(f[2], f[3]); w.z = cvt_pk_bf16(f[4], f[5]); w.w = cvt_pk_bf16(f[6], f[7]); return w; }
; __device__ __forceinline__ f32x16 mfma32(bf16x8 a, bf16x8 b, f32x16 c) { return __builtin_amdgcn_mfma_f32_32x32x16_bf16(a, b, c, 0, 0, 0); }
; __device__ __forceinline__ f32x16 zero16() { return (f32x16){0.f, 0.f, 0.f, 0.f, 0.f, 0.f, 0.f, 0.f, 0.f, 0.f, 0.f, 0.f, 0.f, 0.f, 0.f, 0.f}; }
; __device__ __forceinline__ void r1_item(const bf16_t* __restrict__ projT, bf16_t* stloc, const float* __restrict__ cosT, const float* __restrict__ sinT, float lgf2, float lgb2, int item, int seqlen, LAS unsigned char* lds) {
;     ...
;         float f1[8], f2[8], b1[8], b2[8];
; #pragma unroll
;         for (int j = 0; j < 8; ++j) { const float cv = j < 4 ? c0[j & 3] : c1[j & 3], sv = j < 4 ? s0[j & 3] : s1[j & 3];
;             const float r1 = (k1[j] * cv - k2[j] * sv) * scale, r2 = (k1[j] * sv + k2[j] * cv) * scale;
;             const int tl = 8 * t8 + j; const float df = __builtin_amdgcn_exp2f((float)(127 - tl) * lgf2), db = __builtin_amdgcn_exp2f((float)tl * lgb2);
;             f1[j] = r1 * df; f2[j] = r2 * df; b1[j] = r1 * db; b2[j] = r2 * db; }
;         *(LAS u32x4*)(KTf + d * KT_STRIDE + 8 * t8) = pack8(f1); *(LAS u32x4*)(KTf + (d + 64) * KT_STRIDE + 8 * t8) = pack8(f2);
;         *(LAS u32x4*)(KTb + d * KT_STRIDE + 8 * t8) = pack8(b1); *(LAS u32x4*)(KTb + (d + 64) * KT_STRIDE + 8 * t8) = pack8(b2);
;     }
;     __syncthreads();
; #pragma unroll
;     for (int dir = 0; dir < 2; ++dir) {
;         LAS bf16_t* KT = dir ? KTb : KTf;
;         bf16_t* dst = stloc + ((size_t)(ch * 4 + h) * 2 + dir) * 32768;
; #pragma unroll
;         for (int ct = 0; ct < 4; ++ct) {
;             f32x16 acc = zero16();
; #pragma unroll
;             for (int s = 0; s < 8; ++s) { const bf16x8 bfr = *(const LAS bf16x8*)(KT + (32 * ct + c) * KT_STRIDE + 16 * s + 8 * hh); acc = mfma32(af[s], bfr, acc); }
	v_pk_mul_f32 v[16:17], v[82:83], v[12:13]
	s_nop 0
	v_pk_fma_f32 v[16:17], v[78:79], v[4:5], v[16:17]
	v_pk_mul_f32 v[4:5], v[82:83], v[4:5]
	v_pk_mul_f32 v[16:17], v[16:17], s[64:65] op_sel_hi:[1,0]
	v_pk_fma_f32 v[4:5], v[78:79], v[12:13], v[4:5] neg_lo:[0,0,1] neg_hi:[0,0,1]
	v_pk_mul_f32 v[56:57], v[60:61], v[16:17]
	v_pk_mul_f32 v[4:5], v[4:5], s[64:65] op_sel_hi:[1,0]
	v_pk_mul_f32 v[16:17], v[58:59], v[16:17]
	v_pk_mul_f32 v[12:13], v[60:61], v[4:5]
	v_lshlrev_b32_e32 v60, 16, v71
	v_and_b32_e32 v61, 0xffff0000, v71
	v_pk_mul_f32 v[70:71], v[84:85], v[66:67]
	v_pk_mul_f32 v[58:59], v[58:59], v[4:5]
	v_pk_fma_f32 v[70:71], v[80:81], v[60:61], v[70:71]
	v_pk_mul_f32 v[60:61], v[84:85], v[60:61]
	v_pk_mul_f32 v[70:71], v[70:71], s[64:65] op_sel_hi:[1,0]
	v_pk_fma_f32 v[60:61], v[80:81], v[66:67], v[60:61] neg_lo:[0,0,1] neg_hi:[0,0,1]
	v_lshlrev_b32_e32 v66, 16, v72
	v_and_b32_e32 v67, 0xffff0000, v72
	v_lshlrev_b32_e32 v80, 16, v68
	v_and_b32_e32 v81, 0xffff0000, v68
	v_pk_mul_f32 v[82:83], v[52:53], v[80:81]
	v_pk_mul_f32 v[52:53], v[52:53], v[66:67]
	v_pk_fma_f32 v[82:83], v[74:75], v[66:67], v[82:83]
	v_pk_fma_f32 v[52:53], v[74:75], v[80:81], v[52:53] neg_lo:[0,0,1] neg_hi:[0,0,1]
	v_pk_mul_f32 v[60:61], v[60:61], s[64:65] op_sel_hi:[1,0]
	v_pk_mul_f32 v[82:83], v[82:83], s[64:65] op_sel_hi:[1,0]
	v_pk_mul_f32 v[52:53], v[52:53], s[64:65] op_sel_hi:[1,0]
	v_pk_mul_f32 v[78:79], v[64:65], v[70:71]
	v_pk_mul_f32 v[64:65], v[64:65], v[60:61]
	v_pk_mul_f32 v[84:85], v[6:7], v[82:83]
	v_pk_mul_f32 v[6:7], v[6:7], v[52:53]
	v_pk_mul_f32 v[66:67], v[10:11], v[82:83]
	v_pk_mul_f32 v[10:11], v[10:11], v[52:53]
	v_pk_mul_f32 v[52:53], v[62:63], v[70:71]
	v_pk_mul_f32 v[60:61], v[62:63], v[60:61]
	v_lshlrev_b32_e32 v62, 16, v69
	v_and_b32_e32 v63, 0xffff0000, v69
	v_lshlrev_b32_e32 v4, 16, v73
	v_and_b32_e32 v5, 0xffff0000, v73
	v_pk_mul_f32 v[68:69], v[54:55], v[62:63]
	s_nop 0
	v_pk_fma_f32 v[68:69], v[76:77], v[4:5], v[68:69]
	v_pk_mul_f32 v[4:5], v[54:55], v[4:5]
	v_pk_mul_f32 v[68:69], v[68:69], s[64:65] op_sel_hi:[1,0]
	v_pk_fma_f32 v[4:5], v[76:77], v[62:63], v[4:5] neg_lo:[0,0,1] neg_hi:[0,0,1]
	v_pk_mul_f32 v[70:71], v[2:3], v[68:69]
	v_pk_mul_f32 v[4:5], v[4:5], s[64:65] op_sel_hi:[1,0]
	s_nop 0
	v_pk_mul_f32 v[54:55], v[2:3], v[4:5]
	v_pk_mul_f32 v[62:63], v[14:15], v[4:5]
	v_cvt_pk_bf16_f32 v2, v12, v13
	v_cvt_pk_bf16_f32 v3, v64, v65
	v_cvt_pk_bf16_f32 v4, v6, v7
	v_cvt_pk_bf16_f32 v5, v54, v55
	v_mad_u64_u32 v[6:7], s[10:11], v8, s12, v[50:51]
	ds_write_b128 v6, v[2:5]
	v_cvt_pk_bf16_f32 v2, v56, v57
	v_cvt_pk_bf16_f32 v3, v78, v79
	v_cvt_pk_bf16_f32 v4, v84, v85
	v_cvt_pk_bf16_f32 v5, v70, v71
	v_pk_mul_f32 v[14:15], v[14:15], v[68:69]
	ds_write_b128 v6, v[2:5] offset:17408
	v_cvt_pk_bf16_f32 v2, v58, v59
	v_cvt_pk_bf16_f32 v3, v60, v61
	v_cvt_pk_bf16_f32 v4, v10, v11
	v_cvt_pk_bf16_f32 v5, v62, v63
	v_add_u32_e32 v54, 0, v0
	ds_write_b128 v6, v[2:5] offset:34816
	v_cvt_pk_bf16_f32 v2, v16, v17
	v_cvt_pk_bf16_f32 v3, v52, v53
	v_cvt_pk_bf16_f32 v4, v66, v67
	v_cvt_pk_bf16_f32 v5, v14, v15
	v_mad_u32_u24 v0, v118, s12, v54
	ds_write_b128 v6, v[2:5] offset:52224
	s_waitcnt lgkmcnt(0)
	s_barrier
	ds_read_b128 v[2:5], v0
	ds_read_b128 v[56:59], v0 offset:32
	s_waitcnt lgkmcnt(1)
	v_mfma_f32_32x32x16_bf16 v[2:17], v[46:49], v[2:5], 0
	v_lshlrev_b32_e32 v50, 9, v51
	v_lshl_or_b32 v60, s43, 7, v50
	v_or_b32_e32 v50, v60, v118
	v_ashrrev_i32_e32 v51, 31, v50
	v_lshl_add_u64 v[116:117], v[50:51], 1, s[6:7]
	v_ashrrev_i32_e32 v51, 31, v60
	v_lshl_add_u64 v[52:53], v[50:51], 1, s[6:7]
	s_waitcnt lgkmcnt(0)
	v_mfma_f32_32x32x16_bf16 v[2:17], v[42:45], v[56:59], v[2:17]
	ds_read_b128 v[56:59], v0 offset:64
	v_or_b32_e32 v55, 0x800, v60
	v_or_b32_e32 v121, 0xc80, v60
	v_or_b32_e32 v122, 0xd00, v60
	v_or_b32_e32 v123, 0xd80, v60
	v_or_b32_e32 v51, 32, v118
	v_mad_u32_u24 v120, v51, s12, v54
	s_waitcnt lgkmcnt(0)
	v_mfma_f32_32x32x16_bf16 v[2:17], v[38:41], v[56:59], v[2:17]
	ds_read_b128 v[56:59], v0 offset:96
	s_waitcnt lgkmcnt(0)
	v_mfma_f32_32x32x16_bf16 v[2:17], v[34:37], v[56:59], v[2:17]
	ds_read_b128 v[56:59], v0 offset:128
	s_waitcnt lgkmcnt(0)
	v_mfma_f32_32x32x16_bf16 v[2:17], v[30:33], v[56:59], v[2:17]
	ds_read_b128 v[56:59], v0 offset:160
	s_waitcnt lgkmcnt(0)
	v_mfma_f32_32x32x16_bf16 v[2:17], v[26:29], v[56:59], v[2:17]
	ds_read_b128 v[56:59], v0 offset:192
	s_waitcnt lgkmcnt(0)
	v_mfma_f32_32x32x16_bf16 v[2:17], v[22:25], v[56:59], v[2:17]
	ds_read_b128 v[56:59], v0 offset:224
	s_waitcnt lgkmcnt(0)
; #define LAS __attribute__((address_space(3)))
; __device__ __forceinline__ unsigned cvt_pk_bf16(float lo, float hi) { const f32v2_t v = {lo, hi}; const bf16v2_t r = __builtin_convertvector(v, bf16v2_t); return __builtin_bit_cast(unsigned, r); }
; __device__ __forceinline__ f32x16 mfma32(bf16x8 a, bf16x8 b, f32x16 c) { return __builtin_amdgcn_mfma_f32_32x32x16_bf16(a, b, c, 0, 0, 0); }
; __device__ __forceinline__ f32x16 zero16() { return (f32x16){0.f, 0.f, 0.f, 0.f, 0.f, 0.f, 0.f, 0.f, 0.f, 0.f, 0.f, 0.f, 0.f, 0.f, 0.f, 0.f}; }
; __device__ __forceinline__ void r1_item(const bf16_t* __restrict__ projT, bf16_t* stloc, const float* __restrict__ cosT, const float* __restrict__ sinT, float lgf2, float lgb2, int item, int seqlen, LAS unsigned char* lds) {
;     ...
;         for (int ct = 0; ct < 4; ++ct) {
;             f32x16 acc = zero16();
; #pragma unroll
;             for (int s = 0; s < 8; ++s) { const bf16x8 bfr = *(const LAS bf16x8*)(KT + (32 * ct + c) * KT_STRIDE + 16 * s + 8 * hh); acc = mfma32(af[s], bfr, acc); }
; #pragma unroll
;             for (int rg = 0; rg < 16; ++rg) { const int dv = 32 * w + (rg & 3) + 8 * (rg >> 2) + 4 * hh; dst[dv * 128 + 32 * ct + c] = (bf16_t)(cvt_pk_bf16(acc[rg], 0.f) & 0xffffu); }
	v_mfma_f32_32x32x16_bf16 v[2:17], v[18:21], v[56:59], v[2:17]
	v_or_b32_e32 v56, 0x880, v60
	v_or_b32_e32 v57, 0x900, v60
	v_or_b32_e32 v58, 0x980, v60
	v_or_b32_e32 v59, 0xc00, v60
	s_nop 7
	v_cvt_pk_bf16_f32 v2, v2, s0
	global_store_short v[116:117], v2, off
	v_cvt_pk_bf16_f32 v2, v3, s0
	global_store_short v[52:53], v2, off offset:256
	v_cvt_pk_bf16_f32 v2, v4, s0
	global_store_short v[52:53], v2, off offset:512
	v_cvt_pk_bf16_f32 v2, v5, s0
	global_store_short v[52:53], v2, off offset:768
	v_cvt_pk_bf16_f32 v2, v6, s0
	global_store_short v[52:53], v2, off offset:2048
	v_cvt_pk_bf16_f32 v2, v7, s0
	global_store_short v[52:53], v2, off offset:2304
	v_cvt_pk_bf16_f32 v2, v8, s0
	global_store_short v[52:53], v2, off offset:2560
	v_cvt_pk_bf16_f32 v2, v9, s0
	global_store_short v[52:53], v2, off offset:2816
	v_or_b32_e32 v2, v55, v118
	v_ashrrev_i32_e32 v3, 31, v2
	v_lshl_add_u64 v[100:101], v[2:3], 1, s[6:7]
	v_or_b32_e32 v2, v56, v118
	v_ashrrev_i32_e32 v3, 31, v2
	v_lshl_add_u64 v[102:103], v[2:3], 1, s[6:7]
	v_or_b32_e32 v2, v57, v118
	v_ashrrev_i32_e32 v3, 31, v2
	v_lshl_add_u64 v[104:105], v[2:3], 1, s[6:7]
	v_or_b32_e32 v2, v58, v118
	v_ashrrev_i32_e32 v3, 31, v2
	v_lshl_add_u64 v[106:107], v[2:3], 1, s[6:7]
	v_or_b32_e32 v2, v59, v118
	v_cvt_pk_bf16_f32 v4, v10, s0
	v_ashrrev_i32_e32 v3, 31, v2
	global_store_short v[100:101], v4, off
	v_cvt_pk_bf16_f32 v4, v11, s0
	v_lshl_add_u64 v[108:109], v[2:3], 1, s[6:7]
	v_or_b32_e32 v2, v121, v118
	global_store_short v[102:103], v4, off
	v_cvt_pk_bf16_f32 v4, v12, s0
	v_ashrrev_i32_e32 v3, 31, v2
	global_store_short v[104:105], v4, off
	v_cvt_pk_bf16_f32 v4, v13, s0
	v_lshl_add_u64 v[110:111], v[2:3], 1, s[6:7]
	v_or_b32_e32 v2, v122, v118
	global_store_short v[106:107], v4, off
	v_cvt_pk_bf16_f32 v4, v14, s0
	v_ashrrev_i32_e32 v3, 31, v2
	global_store_short v[108:109], v4, off
	v_cvt_pk_bf16_f32 v4, v15, s0
	v_lshl_add_u64 v[112:113], v[2:3], 1, s[6:7]
	v_or_b32_e32 v2, v123, v118
	global_store_short v[110:111], v4, off
	v_cvt_pk_bf16_f32 v4, v16, s0
	v_ashrrev_i32_e32 v3, 31, v2
	global_store_short v[112:113], v4, off
	v_cvt_pk_bf16_f32 v4, v17, s0
	v_lshl_add_u64 v[114:115], v[2:3], 1, s[6:7]
	global_store_short v[114:115], v4, off
	ds_read_b128 v[2:5], v120
	ds_read_b128 v[60:63], v120 offset:32
	s_waitcnt lgkmcnt(1)
	v_mfma_f32_32x32x16_bf16 v[2:17], v[46:49], v[2:5], 0
	v_add_co_u32_e32 v116, vcc, s26, v116
	s_nop 1
	v_addc_co_u32_e32 v117, vcc, 0, v117, vcc
	s_waitcnt lgkmcnt(0)
	v_mfma_f32_32x32x16_bf16 v[2:17], v[42:45], v[60:63], v[2:17]
	ds_read_b128 v[60:63], v120 offset:64
	s_waitcnt lgkmcnt(0)
	v_mfma_f32_32x32x16_bf16 v[2:17], v[38:41], v[60:63], v[2:17]
	ds_read_b128 v[60:63], v120 offset:96
	s_waitcnt lgkmcnt(0)
	v_mfma_f32_32x32x16_bf16 v[2:17], v[34:37], v[60:63], v[2:17]
	ds_read_b128 v[60:63], v120 offset:128
	s_waitcnt lgkmcnt(0)
	v_mfma_f32_32x32x16_bf16 v[2:17], v[30:33], v[60:63], v[2:17]
	ds_read_b128 v[60:63], v120 offset:160
	s_waitcnt lgkmcnt(0)
	v_mfma_f32_32x32x16_bf16 v[2:17], v[26:29], v[60:63], v[2:17]
	ds_read_b128 v[60:63], v120 offset:192
	s_waitcnt lgkmcnt(0)
	v_mfma_f32_32x32x16_bf16 v[2:17], v[22:25], v[60:63], v[2:17]
	ds_read_b128 v[60:63], v120 offset:224
	s_waitcnt lgkmcnt(0)
	v_mfma_f32_32x32x16_bf16 v[2:17], v[18:21], v[60:63], v[2:17]
	s_nop 11
	v_cvt_pk_bf16_f32 v2, v2, s0
	global_store_short v[52:53], v2, off offset:64
	v_cvt_pk_bf16_f32 v2, v3, s0
	global_store_short v[52:53], v2, off offset:320
	v_cvt_pk_bf16_f32 v2, v4, s0
	global_store_short v[52:53], v2, off offset:576
	v_cvt_pk_bf16_f32 v2, v5, s0
	global_store_short v[52:53], v2, off offset:832
	v_cvt_pk_bf16_f32 v2, v6, s0
	global_store_short v[52:53], v2, off offset:2112
	v_cvt_pk_bf16_f32 v2, v7, s0
	global_store_short v[52:53], v2, off offset:2368
	v_cvt_pk_bf16_f32 v2, v8, s0
	global_store_short v[52:53], v2, off offset:2624
	v_cvt_pk_bf16_f32 v2, v9, s0
	global_store_short v[52:53], v2, off offset:2880
	v_or_b32_e32 v2, v55, v51
	v_ashrrev_i32_e32 v3, 31, v2
	v_lshl_add_u64 v[84:85], v[2:3], 1, s[6:7]
	v_or_b32_e32 v2, v56, v51
	v_ashrrev_i32_e32 v3, 31, v2
	v_lshl_add_u64 v[86:87], v[2:3], 1, s[6:7]
	v_or_b32_e32 v2, v57, v51
	v_ashrrev_i32_e32 v3, 31, v2
	v_lshl_add_u64 v[88:89], v[2:3], 1, s[6:7]
	v_or_b32_e32 v2, v58, v51
	v_ashrrev_i32_e32 v3, 31, v2
	v_lshl_add_u64 v[90:91], v[2:3], 1, s[6:7]
	v_or_b32_e32 v2, v59, v51
	v_cvt_pk_bf16_f32 v4, v10, s0
	v_ashrrev_i32_e32 v3, 31, v2
	global_store_short v[84:85], v4, off
	v_cvt_pk_bf16_f32 v4, v11, s0
	v_lshl_add_u64 v[92:93], v[2:3], 1, s[6:7]
	v_or_b32_e32 v2, v121, v51
	global_store_short v[86:87], v4, off
	v_cvt_pk_bf16_f32 v4, v12, s0
	v_ashrrev_i32_e32 v3, 31, v2
	global_store_short v[88:89], v4, off
	v_cvt_pk_bf16_f32 v4, v13, s0
	v_lshl_add_u64 v[94:95], v[2:3], 1, s[6:7]
	v_or_b32_e32 v2, v122, v51
	global_store_short v[90:91], v4, off
	v_cvt_pk_bf16_f32 v4, v14, s0
	v_ashrrev_i32_e32 v3, 31, v2
	global_store_short v[92:93], v4, off
	v_cvt_pk_bf16_f32 v4, v15, s0
	v_lshl_add_u64 v[96:97], v[2:3], 1, s[6:7]
	v_or_b32_e32 v2, v123, v51
	global_store_short v[94:95], v4, off
	v_cvt_pk_bf16_f32 v4, v16, s0
	v_ashrrev_i32_e32 v3, 31, v2
	global_store_short v[96:97], v4, off
	v_cvt_pk_bf16_f32 v4, v17, s0
	v_lshl_add_u64 v[98:99], v[2:3], 1, s[6:7]
	v_or_b32_e32 v51, 64, v118
	global_store_short v[98:99], v4, off
	v_mad_u32_u24 v119, v51, s12, v54
	ds_read_b128 v[2:5], v119
	ds_read_b128 v[60:63], v119 offset:32
	s_waitcnt lgkmcnt(1)
	v_mfma_f32_32x32x16_bf16 v[2:17], v[46:49], v[2:5], 0
	v_or_b32_e32 v118, 0x60, v118
	s_waitcnt lgkmcnt(0)
	v_mfma_f32_32x32x16_bf16 v[2:17], v[42:45], v[60:63], v[2:17]
	ds_read_b128 v[60:63], v119 offset:64
	s_waitcnt lgkmcnt(0)
; #define LAS __attribute__((address_space(3)))
; __device__ __forceinline__ unsigned cvt_pk_bf16(float lo, float hi) { const f32v2_t v = {lo, hi}; const bf16v2_t r = __builtin_convertvector(v, bf16v2_t); return __builtin_bit_cast(unsigned, r); }
; __device__ __forceinline__ f32x16 mfma32(bf16x8 a, bf16x8 b, f32x16 c) { return __builtin_amdgcn_mfma_f32_32x32x16_bf16(a, b, c, 0, 0, 0); }
; __device__ __forceinline__ f32x16 zero16() { return (f32x16){0.f, 0.f, 0.f, 0.f, 0.f, 0.f, 0.f, 0.f, 0.f, 0.f, 0.f, 0.f, 0.f, 0.f, 0.f, 0.f}; }
; __device__ __forceinline__ void r1_item(const bf16_t* __restrict__ projT, bf16_t* stloc, const float* __restrict__ cosT, const float* __restrict__ sinT, float lgf2, float lgb2, int item, int seqlen, LAS unsigned char* lds) {
;     ...
;         for (int ct = 0; ct < 4; ++ct) {
;             f32x16 acc = zero16();
; #pragma unroll
;             for (int s = 0; s < 8; ++s) { const bf16x8 bfr = *(const LAS bf16x8*)(KT + (32 * ct + c) * KT_STRIDE + 16 * s + 8 * hh); acc = mfma32(af[s], bfr, acc); }
; #pragma unroll
;             for (int rg = 0; rg < 16; ++rg) { const int dv = 32 * w + (rg & 3) + 8 * (rg >> 2) + 4 * hh; dst[dv * 128 + 32 * ct + c] = (bf16_t)(cvt_pk_bf16(acc[rg], 0.f) & 0xffffu); }
	v_mfma_f32_32x32x16_bf16 v[2:17], v[38:41], v[60:63], v[2:17]
	ds_read_b128 v[60:63], v119 offset:96
	s_waitcnt lgkmcnt(0)
	v_mfma_f32_32x32x16_bf16 v[2:17], v[34:37], v[60:63], v[2:17]
	ds_read_b128 v[60:63], v119 offset:128
	s_waitcnt lgkmcnt(0)
	v_mfma_f32_32x32x16_bf16 v[2:17], v[30:33], v[60:63], v[2:17]
	ds_read_b128 v[60:63], v119 offset:160
	s_waitcnt lgkmcnt(0)
	v_mfma_f32_32x32x16_bf16 v[2:17], v[26:29], v[60:63], v[2:17]
	ds_read_b128 v[60:63], v119 offset:192
	s_waitcnt lgkmcnt(0)
	v_mfma_f32_32x32x16_bf16 v[2:17], v[22:25], v[60:63], v[2:17]
	ds_read_b128 v[60:63], v119 offset:224
	s_waitcnt lgkmcnt(0)
	v_mfma_f32_32x32x16_bf16 v[2:17], v[18:21], v[60:63], v[2:17]
	s_nop 11
	v_cvt_pk_bf16_f32 v2, v2, s0
	global_store_short v[52:53], v2, off offset:128
	v_cvt_pk_bf16_f32 v2, v3, s0
	global_store_short v[52:53], v2, off offset:384
	v_cvt_pk_bf16_f32 v2, v4, s0
	global_store_short v[52:53], v2, off offset:640
	v_cvt_pk_bf16_f32 v2, v5, s0
	global_store_short v[52:53], v2, off offset:896
	v_cvt_pk_bf16_f32 v2, v6, s0
	global_store_short v[52:53], v2, off offset:2176
	v_cvt_pk_bf16_f32 v2, v7, s0
	global_store_short v[52:53], v2, off offset:2432
	v_cvt_pk_bf16_f32 v2, v8, s0
	global_store_short v[52:53], v2, off offset:2688
	v_cvt_pk_bf16_f32 v2, v9, s0
	global_store_short v[52:53], v2, off offset:2944
	v_or_b32_e32 v2, v55, v51
	v_ashrrev_i32_e32 v3, 31, v2
	v_lshl_add_u64 v[68:69], v[2:3], 1, s[6:7]
	v_or_b32_e32 v2, v56, v51
	v_ashrrev_i32_e32 v3, 31, v2
	v_lshl_add_u64 v[70:71], v[2:3], 1, s[6:7]
	v_or_b32_e32 v2, v57, v51
	v_ashrrev_i32_e32 v3, 31, v2
	v_lshl_add_u64 v[72:73], v[2:3], 1, s[6:7]
	v_or_b32_e32 v2, v58, v51
	v_ashrrev_i32_e32 v3, 31, v2
	v_lshl_add_u64 v[74:75], v[2:3], 1, s[6:7]
	v_or_b32_e32 v2, v59, v51
	v_cvt_pk_bf16_f32 v4, v10, s0
	v_ashrrev_i32_e32 v3, 31, v2
	global_store_short v[68:69], v4, off
	v_cvt_pk_bf16_f32 v4, v11, s0
	v_lshl_add_u64 v[76:77], v[2:3], 1, s[6:7]
	v_or_b32_e32 v2, v121, v51
	global_store_short v[70:71], v4, off
	v_cvt_pk_bf16_f32 v4, v12, s0
	v_ashrrev_i32_e32 v3, 31, v2
	global_store_short v[72:73], v4, off
	v_cvt_pk_bf16_f32 v4, v13, s0
	v_lshl_add_u64 v[78:79], v[2:3], 1, s[6:7]
	v_or_b32_e32 v2, v122, v51
	global_store_short v[74:75], v4, off
	v_cvt_pk_bf16_f32 v4, v14, s0
	v_ashrrev_i32_e32 v3, 31, v2
	global_store_short v[76:77], v4, off
	v_cvt_pk_bf16_f32 v4, v15, s0
	v_lshl_add_u64 v[80:81], v[2:3], 1, s[6:7]
	v_or_b32_e32 v2, v123, v51
	global_store_short v[78:79], v4, off
	v_cvt_pk_bf16_f32 v4, v16, s0
	v_ashrrev_i32_e32 v3, 31, v2
	global_store_short v[80:81], v4, off
	v_cvt_pk_bf16_f32 v4, v17, s0
	v_lshl_add_u64 v[82:83], v[2:3], 1, s[6:7]
	global_store_short v[82:83], v4, off
	v_mad_u32_u24 v51, v118, s12, v54
	ds_read_b128 v[2:5], v51
	ds_read_b128 v[60:63], v51 offset:32
	s_waitcnt lgkmcnt(1)
	v_mfma_f32_32x32x16_bf16 v[2:17], v[46:49], v[2:5], 0
	s_waitcnt lgkmcnt(0)
	v_mfma_f32_32x32x16_bf16 v[2:17], v[42:45], v[60:63], v[2:17]
	ds_read_b128 v[60:63], v51 offset:64
	s_waitcnt lgkmcnt(0)
	v_mfma_f32_32x32x16_bf16 v[2:17], v[38:41], v[60:63], v[2:17]
	ds_read_b128 v[60:63], v51 offset:96
	s_waitcnt lgkmcnt(0)
	v_mfma_f32_32x32x16_bf16 v[2:17], v[34:37], v[60:63], v[2:17]
	ds_read_b128 v[60:63], v51 offset:128
	s_waitcnt lgkmcnt(0)
	v_mfma_f32_32x32x16_bf16 v[2:17], v[30:33], v[60:63], v[2:17]
	ds_read_b128 v[60:63], v51 offset:160
	s_waitcnt lgkmcnt(0)
	v_mfma_f32_32x32x16_bf16 v[2:17], v[26:29], v[60:63], v[2:17]
	ds_read_b128 v[60:63], v51 offset:192
	s_waitcnt lgkmcnt(0)
	v_mfma_f32_32x32x16_bf16 v[2:17], v[22:25], v[60:63], v[2:17]
	ds_read_b128 v[60:63], v51 offset:224
	s_waitcnt lgkmcnt(0)
	v_mfma_f32_32x32x16_bf16 v[2:17], v[18:21], v[60:63], v[2:17]
	s_nop 11
	v_cvt_pk_bf16_f32 v2, v2, s0
	global_store_short v[52:53], v2, off offset:192
	v_cvt_pk_bf16_f32 v2, v3, s0
	global_store_short v[52:53], v2, off offset:448
	v_cvt_pk_bf16_f32 v2, v4, s0
	global_store_short v[52:53], v2, off offset:704
	v_cvt_pk_bf16_f32 v2, v5, s0
	global_store_short v[52:53], v2, off offset:960
	v_cvt_pk_bf16_f32 v2, v6, s0
	global_store_short v[52:53], v2, off offset:2240
	v_cvt_pk_bf16_f32 v2, v7, s0
	global_store_short v[52:53], v2, off offset:2496
	v_cvt_pk_bf16_f32 v2, v8, s0
	global_store_short v[52:53], v2, off offset:2752
	v_cvt_pk_bf16_f32 v2, v9, s0
	global_store_short v[52:53], v2, off offset:3008
	v_or_b32_e32 v2, v55, v118
	v_ashrrev_i32_e32 v3, 31, v2
	v_lshl_add_u64 v[66:67], v[2:3], 1, s[6:7]
	v_or_b32_e32 v2, v56, v118
	v_ashrrev_i32_e32 v3, 31, v2
	v_lshl_add_u64 v[64:65], v[2:3], 1, s[6:7]
	v_or_b32_e32 v2, v57, v118
	v_ashrrev_i32_e32 v3, 31, v2
	v_lshl_add_u64 v[62:63], v[2:3], 1, s[6:7]
	v_or_b32_e32 v2, v58, v118
	v_ashrrev_i32_e32 v3, 31, v2
	v_lshl_add_u64 v[60:61], v[2:3], 1, s[6:7]
	v_or_b32_e32 v2, v59, v118
	v_cvt_pk_bf16_f32 v4, v10, s0
	v_ashrrev_i32_e32 v3, 31, v2
	global_store_short v[66:67], v4, off
	v_cvt_pk_bf16_f32 v4, v11, s0
	v_lshl_add_u64 v[58:59], v[2:3], 1, s[6:7]
	v_or_b32_e32 v2, v121, v118
	global_store_short v[64:65], v4, off
	v_cvt_pk_bf16_f32 v4, v12, s0
	v_ashrrev_i32_e32 v3, 31, v2
	global_store_short v[62:63], v4, off
	v_cvt_pk_bf16_f32 v4, v13, s0
	v_lshl_add_u64 v[56:57], v[2:3], 1, s[6:7]
	v_or_b32_e32 v2, v122, v118
	global_store_short v[60:61], v4, off
	v_cvt_pk_bf16_f32 v4, v14, s0
	v_ashrrev_i32_e32 v3, 31, v2
	global_store_short v[58:59], v4, off
	v_cvt_pk_bf16_f32 v4, v15, s0
	v_lshl_add_u64 v[54:55], v[2:3], 1, s[6:7]
	v_or_b32_e32 v2, v123, v118
	global_store_short v[56:57], v4, off
	v_cvt_pk_bf16_f32 v4, v16, s0
	v_ashrrev_i32_e32 v3, 31, v2
	global_store_short v[54:55], v4, off
	v_cvt_pk_bf16_f32 v4, v17, s0
	v_lshl_add_u64 v[52:53], v[2:3], 1, s[6:7]
	global_store_short v[52:53], v4, off
	ds_read_b128 v[2:5], v0 offset:34816
	ds_read_b128 v[122:125], v0 offset:34848
	s_waitcnt lgkmcnt(1)
; #define LAS __attribute__((address_space(3)))
; __device__ __forceinline__ unsigned cvt_pk_bf16(float lo, float hi) { const f32v2_t v = {lo, hi}; const bf16v2_t r = __builtin_convertvector(v, bf16v2_t); return __builtin_bit_cast(unsigned, r); }
; __device__ __forceinline__ f32x16 mfma32(bf16x8 a, bf16x8 b, f32x16 c) { return __builtin_amdgcn_mfma_f32_32x32x16_bf16(a, b, c, 0, 0, 0); }
; __device__ __forceinline__ f32x16 zero16() { return (f32x16){0.f, 0.f, 0.f, 0.f, 0.f, 0.f, 0.f, 0.f, 0.f, 0.f, 0.f, 0.f, 0.f, 0.f, 0.f, 0.f}; }
; __device__ __forceinline__ void r1_item(const bf16_t* __restrict__ projT, bf16_t* stloc, const float* __restrict__ cosT, const float* __restrict__ sinT, float lgf2, float lgb2, int item, int seqlen, LAS unsigned char* lds) {
;     ...
;     for (int dir = 0; dir < 2; ++dir) {
;         LAS bf16_t* KT = dir ? KTb : KTf;
;         bf16_t* dst = stloc + ((size_t)(ch * 4 + h) * 2 + dir) * 32768;
; #pragma unroll
;         for (int ct = 0; ct < 4; ++ct) {
;             f32x16 acc = zero16();
; #pragma unroll
;             for (int s = 0; s < 8; ++s) { const bf16x8 bfr = *(const LAS bf16x8*)(KT + (32 * ct + c) * KT_STRIDE + 16 * s + 8 * hh); acc = mfma32(af[s], bfr, acc); }
; #pragma unroll
;             for (int rg = 0; rg < 16; ++rg) { const int dv = 32 * w + (rg & 3) + 8 * (rg >> 2) + 4 * hh; dst[dv * 128 + 32 * ct + c] = (bf16_t)(cvt_pk_bf16(acc[rg], 0.f) & 0xffffu); }
	v_mfma_f32_32x32x16_bf16 v[2:17], v[46:49], v[2:5], 0
	s_waitcnt lgkmcnt(0)
	v_mfma_f32_32x32x16_bf16 v[2:17], v[42:45], v[122:125], v[2:17]
	ds_read_b128 v[122:125], v0 offset:34880
	s_waitcnt lgkmcnt(0)
	v_mfma_f32_32x32x16_bf16 v[2:17], v[38:41], v[122:125], v[2:17]
	ds_read_b128 v[122:125], v0 offset:34912
	s_waitcnt lgkmcnt(0)
	v_mfma_f32_32x32x16_bf16 v[2:17], v[34:37], v[122:125], v[2:17]
	ds_read_b128 v[122:125], v0 offset:34944
	s_waitcnt lgkmcnt(0)
	v_mfma_f32_32x32x16_bf16 v[2:17], v[30:33], v[122:125], v[2:17]
	ds_read_b128 v[122:125], v0 offset:34976
	s_waitcnt lgkmcnt(0)
	v_mfma_f32_32x32x16_bf16 v[2:17], v[26:29], v[122:125], v[2:17]
	ds_read_b128 v[122:125], v0 offset:35008
	s_waitcnt lgkmcnt(0)
	v_mfma_f32_32x32x16_bf16 v[2:17], v[22:25], v[122:125], v[2:17]
	ds_read_b128 v[122:125], v0 offset:35040
	s_waitcnt lgkmcnt(0)
	v_mfma_f32_32x32x16_bf16 v[2:17], v[18:21], v[122:125], v[2:17]
	s_nop 11
	v_cvt_pk_bf16_f32 v0, v2, s0
	v_or_b32_e32 v2, 0x80, v50
	global_store_short v[116:117], v0, off
	v_cvt_pk_bf16_f32 v0, v3, s0
	v_ashrrev_i32_e32 v3, 31, v2
	v_lshl_add_u64 v[2:3], v[2:3], 1, s[6:7]
	v_add_co_u32_e32 v2, vcc, s26, v2
	s_nop 1
	v_addc_co_u32_e32 v3, vcc, 0, v3, vcc
	global_store_short v[2:3], v0, off
	v_or_b32_e32 v2, 0x100, v50
	v_ashrrev_i32_e32 v3, 31, v2
	v_lshl_add_u64 v[2:3], v[2:3], 1, s[6:7]
	v_add_co_u32_e32 v2, vcc, s26, v2
	v_cvt_pk_bf16_f32 v0, v4, s0
	s_nop 0
	v_addc_co_u32_e32 v3, vcc, 0, v3, vcc
	global_store_short v[2:3], v0, off
	v_or_b32_e32 v2, 0x180, v50
	v_ashrrev_i32_e32 v3, 31, v2
	v_lshl_add_u64 v[2:3], v[2:3], 1, s[6:7]
	v_add_co_u32_e32 v2, vcc, s26, v2
	v_cvt_pk_bf16_f32 v0, v5, s0
	s_nop 0
	v_addc_co_u32_e32 v3, vcc, 0, v3, vcc
	global_store_short v[2:3], v0, off
	v_or_b32_e32 v2, 0x400, v50
	v_ashrrev_i32_e32 v3, 31, v2
	v_lshl_add_u64 v[2:3], v[2:3], 1, s[6:7]
	v_add_co_u32_e32 v2, vcc, s26, v2
	v_cvt_pk_bf16_f32 v0, v6, s0
	s_nop 0
	v_addc_co_u32_e32 v3, vcc, 0, v3, vcc
	global_store_short v[2:3], v0, off
	v_or_b32_e32 v2, 0x480, v50
	v_ashrrev_i32_e32 v3, 31, v2
	v_lshl_add_u64 v[2:3], v[2:3], 1, s[6:7]
	v_add_co_u32_e32 v2, vcc, s26, v2
	v_cvt_pk_bf16_f32 v0, v7, s0
	s_nop 0
	v_addc_co_u32_e32 v3, vcc, 0, v3, vcc
	global_store_short v[2:3], v0, off
	v_or_b32_e32 v2, 0x500, v50
	v_ashrrev_i32_e32 v3, 31, v2
	v_lshl_add_u64 v[2:3], v[2:3], 1, s[6:7]
	v_add_co_u32_e32 v2, vcc, s26, v2
	v_cvt_pk_bf16_f32 v0, v8, s0
	s_nop 0
	v_addc_co_u32_e32 v3, vcc, 0, v3, vcc
	global_store_short v[2:3], v0, off
	v_or_b32_e32 v2, 0x580, v50
	v_ashrrev_i32_e32 v3, 31, v2
	v_lshl_add_u64 v[2:3], v[2:3], 1, s[6:7]
	v_add_co_u32_e32 v2, vcc, s26, v2
	v_cvt_pk_bf16_f32 v0, v9, s0
	s_nop 0
	v_addc_co_u32_e32 v3, vcc, 0, v3, vcc
	global_store_short v[2:3], v0, off
	v_add_co_u32_e32 v2, vcc, s26, v100
	v_cvt_pk_bf16_f32 v0, v10, s0
	s_nop 0
	v_addc_co_u32_e32 v3, vcc, 0, v101, vcc
	global_store_short v[2:3], v0, off
	v_add_co_u32_e32 v2, vcc, s26, v102
	v_cvt_pk_bf16_f32 v0, v11, s0
	s_nop 0
	v_addc_co_u32_e32 v3, vcc, 0, v103, vcc
	global_store_short v[2:3], v0, off
	v_add_co_u32_e32 v2, vcc, s26, v104
	v_cvt_pk_bf16_f32 v0, v12, s0
	s_nop 0
	v_addc_co_u32_e32 v3, vcc, 0, v105, vcc
	global_store_short v[2:3], v0, off
	v_add_co_u32_e32 v2, vcc, s26, v106
	v_cvt_pk_bf16_f32 v0, v13, s0
	s_nop 0
	v_addc_co_u32_e32 v3, vcc, 0, v107, vcc
	global_store_short v[2:3], v0, off
	v_add_co_u32_e32 v2, vcc, s26, v108
	v_cvt_pk_bf16_f32 v0, v14, s0
	s_nop 0
	v_addc_co_u32_e32 v3, vcc, 0, v109, vcc
	global_store_short v[2:3], v0, off
	v_add_co_u32_e32 v2, vcc, s26, v110
	v_cvt_pk_bf16_f32 v0, v15, s0
	s_nop 0
	v_addc_co_u32_e32 v3, vcc, 0, v111, vcc
	global_store_short v[2:3], v0, off
	v_add_co_u32_e32 v2, vcc, s26, v112
	v_cvt_pk_bf16_f32 v0, v16, s0
	s_nop 0
	v_addc_co_u32_e32 v3, vcc, 0, v113, vcc
	global_store_short v[2:3], v0, off
	v_add_co_u32_e32 v2, vcc, s26, v114
	v_cvt_pk_bf16_f32 v0, v17, s0
	s_nop 0
	v_addc_co_u32_e32 v3, vcc, 0, v115, vcc
	global_store_short v[2:3], v0, off
	ds_read_b128 v[2:5], v120 offset:34816
	ds_read_b128 v[100:103], v120 offset:34848
	s_waitcnt lgkmcnt(1)
	v_mfma_f32_32x32x16_bf16 v[2:17], v[46:49], v[2:5], 0
	s_waitcnt lgkmcnt(0)
	v_mfma_f32_32x32x16_bf16 v[2:17], v[42:45], v[100:103], v[2:17]
	ds_read_b128 v[100:103], v120 offset:34880
	s_waitcnt lgkmcnt(0)
	v_mfma_f32_32x32x16_bf16 v[2:17], v[38:41], v[100:103], v[2:17]
	ds_read_b128 v[100:103], v120 offset:34912
	s_waitcnt lgkmcnt(0)
	v_mfma_f32_32x32x16_bf16 v[2:17], v[34:37], v[100:103], v[2:17]
	ds_read_b128 v[100:103], v120 offset:34944
	s_waitcnt lgkmcnt(0)
	v_mfma_f32_32x32x16_bf16 v[2:17], v[30:33], v[100:103], v[2:17]
	ds_read_b128 v[100:103], v120 offset:34976
	s_waitcnt lgkmcnt(0)
	v_mfma_f32_32x32x16_bf16 v[2:17], v[26:29], v[100:103], v[2:17]
	ds_read_b128 v[100:103], v120 offset:35008
	s_waitcnt lgkmcnt(0)
	v_mfma_f32_32x32x16_bf16 v[2:17], v[22:25], v[100:103], v[2:17]
	ds_read_b128 v[100:103], v120 offset:35040
	s_waitcnt lgkmcnt(0)
; #define LAS __attribute__((address_space(3)))
; __device__ __forceinline__ unsigned cvt_pk_bf16(float lo, float hi) { const f32v2_t v = {lo, hi}; const bf16v2_t r = __builtin_convertvector(v, bf16v2_t); return __builtin_bit_cast(unsigned, r); }
; __device__ __forceinline__ f32x16 mfma32(bf16x8 a, bf16x8 b, f32x16 c) { return __builtin_amdgcn_mfma_f32_32x32x16_bf16(a, b, c, 0, 0, 0); }
; __device__ __forceinline__ f32x16 zero16() { return (f32x16){0.f, 0.f, 0.f, 0.f, 0.f, 0.f, 0.f, 0.f, 0.f, 0.f, 0.f, 0.f, 0.f, 0.f, 0.f, 0.f}; }
; __device__ __forceinline__ void r1_item(const bf16_t* __restrict__ projT, bf16_t* stloc, const float* __restrict__ cosT, const float* __restrict__ sinT, float lgf2, float lgb2, int item, int seqlen, LAS unsigned char* lds) {
;     ...
;         for (int ct = 0; ct < 4; ++ct) {
;             f32x16 acc = zero16();
; #pragma unroll
;             for (int s = 0; s < 8; ++s) { const bf16x8 bfr = *(const LAS bf16x8*)(KT + (32 * ct + c) * KT_STRIDE + 16 * s + 8 * hh); acc = mfma32(af[s], bfr, acc); }
; #pragma unroll
;             for (int rg = 0; rg < 16; ++rg) { const int dv = 32 * w + (rg & 3) + 8 * (rg >> 2) + 4 * hh; dst[dv * 128 + 32 * ct + c] = (bf16_t)(cvt_pk_bf16(acc[rg], 0.f) & 0xffffu); }
	v_mfma_f32_32x32x16_bf16 v[2:17], v[18:21], v[100:103], v[2:17]
	v_or_b32_e32 v100, 32, v50
	v_ashrrev_i32_e32 v101, 31, v100
	v_lshl_add_u64 v[100:101], v[100:101], 1, s[6:7]
	v_add_co_u32_e32 v100, vcc, s26, v100
	s_nop 1
	v_addc_co_u32_e32 v101, vcc, 0, v101, vcc
	s_nop 4
	v_cvt_pk_bf16_f32 v0, v2, s0
	v_or_b32_e32 v2, 0xa0, v50
	global_store_short v[100:101], v0, off
	v_cvt_pk_bf16_f32 v0, v3, s0
	v_ashrrev_i32_e32 v3, 31, v2
	v_lshl_add_u64 v[2:3], v[2:3], 1, s[6:7]
	v_add_co_u32_e32 v2, vcc, s26, v2
	s_nop 1
	v_addc_co_u32_e32 v3, vcc, 0, v3, vcc
	global_store_short v[2:3], v0, off
	v_or_b32_e32 v2, 0x120, v50
	v_ashrrev_i32_e32 v3, 31, v2
	v_lshl_add_u64 v[2:3], v[2:3], 1, s[6:7]
	v_add_co_u32_e32 v2, vcc, s26, v2
	v_cvt_pk_bf16_f32 v0, v4, s0
	s_nop 0
	v_addc_co_u32_e32 v3, vcc, 0, v3, vcc
	global_store_short v[2:3], v0, off
	v_or_b32_e32 v2, 0x1a0, v50
	v_ashrrev_i32_e32 v3, 31, v2
	v_lshl_add_u64 v[2:3], v[2:3], 1, s[6:7]
	v_add_co_u32_e32 v2, vcc, s26, v2
	v_cvt_pk_bf16_f32 v0, v5, s0
	s_nop 0
	v_addc_co_u32_e32 v3, vcc, 0, v3, vcc
	global_store_short v[2:3], v0, off
	v_or_b32_e32 v2, 0x420, v50
	v_ashrrev_i32_e32 v3, 31, v2
	v_lshl_add_u64 v[2:3], v[2:3], 1, s[6:7]
	v_add_co_u32_e32 v2, vcc, s26, v2
	v_cvt_pk_bf16_f32 v0, v6, s0
	s_nop 0
	v_addc_co_u32_e32 v3, vcc, 0, v3, vcc
	global_store_short v[2:3], v0, off
	v_or_b32_e32 v2, 0x4a0, v50
	v_ashrrev_i32_e32 v3, 31, v2
	v_lshl_add_u64 v[2:3], v[2:3], 1, s[6:7]
	v_add_co_u32_e32 v2, vcc, s26, v2
	v_cvt_pk_bf16_f32 v0, v7, s0
	s_nop 0
	v_addc_co_u32_e32 v3, vcc, 0, v3, vcc
	global_store_short v[2:3], v0, off
	v_or_b32_e32 v2, 0x520, v50
	v_ashrrev_i32_e32 v3, 31, v2
	v_lshl_add_u64 v[2:3], v[2:3], 1, s[6:7]
	v_add_co_u32_e32 v2, vcc, s26, v2
	v_cvt_pk_bf16_f32 v0, v8, s0
	s_nop 0
	v_addc_co_u32_e32 v3, vcc, 0, v3, vcc
	global_store_short v[2:3], v0, off
	v_or_b32_e32 v2, 0x5a0, v50
	v_ashrrev_i32_e32 v3, 31, v2
	v_lshl_add_u64 v[2:3], v[2:3], 1, s[6:7]
	v_add_co_u32_e32 v2, vcc, s26, v2
	v_cvt_pk_bf16_f32 v0, v9, s0
	s_nop 0
	v_addc_co_u32_e32 v3, vcc, 0, v3, vcc
	global_store_short v[2:3], v0, off
	v_add_co_u32_e32 v2, vcc, s26, v84
	v_cvt_pk_bf16_f32 v0, v10, s0
	s_nop 0
	v_addc_co_u32_e32 v3, vcc, 0, v85, vcc
	global_store_short v[2:3], v0, off
	v_add_co_u32_e32 v2, vcc, s26, v86
	v_cvt_pk_bf16_f32 v0, v11, s0
	s_nop 0
	v_addc_co_u32_e32 v3, vcc, 0, v87, vcc
	global_store_short v[2:3], v0, off
	v_add_co_u32_e32 v2, vcc, s26, v88
	v_cvt_pk_bf16_f32 v0, v12, s0
	s_nop 0
	v_addc_co_u32_e32 v3, vcc, 0, v89, vcc
	global_store_short v[2:3], v0, off
	v_add_co_u32_e32 v2, vcc, s26, v90
	v_cvt_pk_bf16_f32 v0, v13, s0
	s_nop 0
	v_addc_co_u32_e32 v3, vcc, 0, v91, vcc
	global_store_short v[2:3], v0, off
	v_add_co_u32_e32 v2, vcc, s26, v92
	v_cvt_pk_bf16_f32 v0, v14, s0
	s_nop 0
	v_addc_co_u32_e32 v3, vcc, 0, v93, vcc
	global_store_short v[2:3], v0, off
	v_add_co_u32_e32 v2, vcc, s26, v94
	v_cvt_pk_bf16_f32 v0, v15, s0
	s_nop 0
	v_addc_co_u32_e32 v3, vcc, 0, v95, vcc
	global_store_short v[2:3], v0, off
	v_add_co_u32_e32 v2, vcc, s26, v96
	v_cvt_pk_bf16_f32 v0, v16, s0
	s_nop 0
	v_addc_co_u32_e32 v3, vcc, 0, v97, vcc
	global_store_short v[2:3], v0, off
	v_add_co_u32_e32 v2, vcc, s26, v98
	v_cvt_pk_bf16_f32 v0, v17, s0
	s_nop 0
	v_addc_co_u32_e32 v3, vcc, 0, v99, vcc
	global_store_short v[2:3], v0, off
	ds_read_b128 v[2:5], v119 offset:34816
	ds_read_b128 v[84:87], v119 offset:34848
	s_waitcnt lgkmcnt(1)
	v_mfma_f32_32x32x16_bf16 v[2:17], v[46:49], v[2:5], 0
	s_waitcnt lgkmcnt(0)
	v_mfma_f32_32x32x16_bf16 v[2:17], v[42:45], v[84:87], v[2:17]
	ds_read_b128 v[84:87], v119 offset:34880
	s_waitcnt lgkmcnt(0)
	v_mfma_f32_32x32x16_bf16 v[2:17], v[38:41], v[84:87], v[2:17]
	ds_read_b128 v[84:87], v119 offset:34912
	s_waitcnt lgkmcnt(0)
	v_mfma_f32_32x32x16_bf16 v[2:17], v[34:37], v[84:87], v[2:17]
	ds_read_b128 v[84:87], v119 offset:34944
	s_waitcnt lgkmcnt(0)
	v_mfma_f32_32x32x16_bf16 v[2:17], v[30:33], v[84:87], v[2:17]
	ds_read_b128 v[84:87], v119 offset:34976
	s_waitcnt lgkmcnt(0)
	v_mfma_f32_32x32x16_bf16 v[2:17], v[26:29], v[84:87], v[2:17]
	ds_read_b128 v[84:87], v119 offset:35008
	s_waitcnt lgkmcnt(0)
	v_mfma_f32_32x32x16_bf16 v[2:17], v[22:25], v[84:87], v[2:17]
	ds_read_b128 v[84:87], v119 offset:35040
	s_waitcnt lgkmcnt(0)
; #define LAS __attribute__((address_space(3)))
; __device__ __forceinline__ unsigned cvt_pk_bf16(float lo, float hi) { const f32v2_t v = {lo, hi}; const bf16v2_t r = __builtin_convertvector(v, bf16v2_t); return __builtin_bit_cast(unsigned, r); }
; __device__ __forceinline__ f32x16 mfma32(bf16x8 a, bf16x8 b, f32x16 c) { return __builtin_amdgcn_mfma_f32_32x32x16_bf16(a, b, c, 0, 0, 0); }
; __device__ __forceinline__ f32x16 zero16() { return (f32x16){0.f, 0.f, 0.f, 0.f, 0.f, 0.f, 0.f, 0.f, 0.f, 0.f, 0.f, 0.f, 0.f, 0.f, 0.f, 0.f}; }
; __device__ __forceinline__ void r1_item(const bf16_t* __restrict__ projT, bf16_t* stloc, const float* __restrict__ cosT, const float* __restrict__ sinT, float lgf2, float lgb2, int item, int seqlen, LAS unsigned char* lds) {
;     ...
;         for (int ct = 0; ct < 4; ++ct) {
;             f32x16 acc = zero16();
; #pragma unroll
;             for (int s = 0; s < 8; ++s) { const bf16x8 bfr = *(const LAS bf16x8*)(KT + (32 * ct + c) * KT_STRIDE + 16 * s + 8 * hh); acc = mfma32(af[s], bfr, acc); }
; #pragma unroll
;             for (int rg = 0; rg < 16; ++rg) { const int dv = 32 * w + (rg & 3) + 8 * (rg >> 2) + 4 * hh; dst[dv * 128 + 32 * ct + c] = (bf16_t)(cvt_pk_bf16(acc[rg], 0.f) & 0xffffu); }
	v_mfma_f32_32x32x16_bf16 v[2:17], v[18:21], v[84:87], v[2:17]
	v_or_b32_e32 v84, 64, v50
	v_ashrrev_i32_e32 v85, 31, v84
	v_lshl_add_u64 v[84:85], v[84:85], 1, s[6:7]
	v_add_co_u32_e32 v84, vcc, s26, v84
	s_nop 1
	v_addc_co_u32_e32 v85, vcc, 0, v85, vcc
	s_nop 4
	v_cvt_pk_bf16_f32 v0, v2, s0
	v_or_b32_e32 v2, 0xc0, v50
	global_store_short v[84:85], v0, off
	v_cvt_pk_bf16_f32 v0, v3, s0
	v_ashrrev_i32_e32 v3, 31, v2
	v_lshl_add_u64 v[2:3], v[2:3], 1, s[6:7]
	v_add_co_u32_e32 v2, vcc, s26, v2
	s_nop 1
	v_addc_co_u32_e32 v3, vcc, 0, v3, vcc
	global_store_short v[2:3], v0, off
	v_or_b32_e32 v2, 0x140, v50
	v_ashrrev_i32_e32 v3, 31, v2
	v_lshl_add_u64 v[2:3], v[2:3], 1, s[6:7]
	v_add_co_u32_e32 v2, vcc, s26, v2
	v_cvt_pk_bf16_f32 v0, v4, s0
	s_nop 0
	v_addc_co_u32_e32 v3, vcc, 0, v3, vcc
	global_store_short v[2:3], v0, off
	v_or_b32_e32 v2, 0x1c0, v50
	v_ashrrev_i32_e32 v3, 31, v2
	v_lshl_add_u64 v[2:3], v[2:3], 1, s[6:7]
	v_add_co_u32_e32 v2, vcc, s26, v2
	v_cvt_pk_bf16_f32 v0, v5, s0
	s_nop 0
	v_addc_co_u32_e32 v3, vcc, 0, v3, vcc
	global_store_short v[2:3], v0, off
	v_or_b32_e32 v2, 0x440, v50
	v_ashrrev_i32_e32 v3, 31, v2
	v_lshl_add_u64 v[2:3], v[2:3], 1, s[6:7]
	v_add_co_u32_e32 v2, vcc, s26, v2
	v_cvt_pk_bf16_f32 v0, v6, s0
	s_nop 0
	v_addc_co_u32_e32 v3, vcc, 0, v3, vcc
	global_store_short v[2:3], v0, off
	v_or_b32_e32 v2, 0x4c0, v50
	v_ashrrev_i32_e32 v3, 31, v2
	v_lshl_add_u64 v[2:3], v[2:3], 1, s[6:7]
	v_add_co_u32_e32 v2, vcc, s26, v2
	v_cvt_pk_bf16_f32 v0, v7, s0
	s_nop 0
	v_addc_co_u32_e32 v3, vcc, 0, v3, vcc
	global_store_short v[2:3], v0, off
	v_or_b32_e32 v2, 0x540, v50
	v_ashrrev_i32_e32 v3, 31, v2
	v_lshl_add_u64 v[2:3], v[2:3], 1, s[6:7]
	v_add_co_u32_e32 v2, vcc, s26, v2
	v_cvt_pk_bf16_f32 v0, v8, s0
	s_nop 0
	v_addc_co_u32_e32 v3, vcc, 0, v3, vcc
	global_store_short v[2:3], v0, off
	v_or_b32_e32 v2, 0x5c0, v50
	v_ashrrev_i32_e32 v3, 31, v2
	v_lshl_add_u64 v[2:3], v[2:3], 1, s[6:7]
	v_add_co_u32_e32 v2, vcc, s26, v2
	v_cvt_pk_bf16_f32 v0, v9, s0
	s_nop 0
	v_addc_co_u32_e32 v3, vcc, 0, v3, vcc
	global_store_short v[2:3], v0, off
	v_add_co_u32_e32 v2, vcc, s26, v68
	v_cvt_pk_bf16_f32 v0, v10, s0
	s_nop 0
	v_addc_co_u32_e32 v3, vcc, 0, v69, vcc
	global_store_short v[2:3], v0, off
	v_add_co_u32_e32 v2, vcc, s26, v70
	v_cvt_pk_bf16_f32 v0, v11, s0
	s_nop 0
	v_addc_co_u32_e32 v3, vcc, 0, v71, vcc
	global_store_short v[2:3], v0, off
	v_add_co_u32_e32 v2, vcc, s26, v72
	v_cvt_pk_bf16_f32 v0, v12, s0
	s_nop 0
	v_addc_co_u32_e32 v3, vcc, 0, v73, vcc
	global_store_short v[2:3], v0, off
	v_add_co_u32_e32 v2, vcc, s26, v74
	v_cvt_pk_bf16_f32 v0, v13, s0
	s_nop 0
	v_addc_co_u32_e32 v3, vcc, 0, v75, vcc
	global_store_short v[2:3], v0, off
	v_add_co_u32_e32 v2, vcc, s26, v76
	v_cvt_pk_bf16_f32 v0, v14, s0
	s_nop 0
	v_addc_co_u32_e32 v3, vcc, 0, v77, vcc
	global_store_short v[2:3], v0, off
	v_add_co_u32_e32 v2, vcc, s26, v78
	v_cvt_pk_bf16_f32 v0, v15, s0
	s_nop 0
	v_addc_co_u32_e32 v3, vcc, 0, v79, vcc
	global_store_short v[2:3], v0, off
	v_add_co_u32_e32 v2, vcc, s26, v80
	v_cvt_pk_bf16_f32 v0, v16, s0
	s_nop 0
	v_addc_co_u32_e32 v3, vcc, 0, v81, vcc
	global_store_short v[2:3], v0, off
	v_add_co_u32_e32 v2, vcc, s26, v82
	v_cvt_pk_bf16_f32 v0, v17, s0
	s_nop 0
	v_addc_co_u32_e32 v3, vcc, 0, v83, vcc
	global_store_short v[2:3], v0, off
	ds_read_b128 v[2:5], v51 offset:34816
	ds_read_b128 v[68:71], v51 offset:34848
	s_waitcnt lgkmcnt(1)
	v_mfma_f32_32x32x16_bf16 v[2:17], v[46:49], v[2:5], 0
	s_waitcnt lgkmcnt(0)
	v_mfma_f32_32x32x16_bf16 v[2:17], v[42:45], v[68:71], v[2:17]
	ds_read_b128 v[42:45], v51 offset:34880
	s_waitcnt lgkmcnt(0)
	v_mfma_f32_32x32x16_bf16 v[2:17], v[38:41], v[42:45], v[2:17]
	ds_read_b128 v[38:41], v51 offset:34912
	s_waitcnt lgkmcnt(0)
	v_mfma_f32_32x32x16_bf16 v[2:17], v[34:37], v[38:41], v[2:17]
	ds_read_b128 v[34:37], v51 offset:34944
	s_waitcnt lgkmcnt(0)
; #define LAS __attribute__((address_space(3)))
; __device__ __forceinline__ unsigned cvt_pk_bf16(float lo, float hi) { const f32v2_t v = {lo, hi}; const bf16v2_t r = __builtin_convertvector(v, bf16v2_t); return __builtin_bit_cast(unsigned, r); }
; __device__ __forceinline__ f32x16 mfma32(bf16x8 a, bf16x8 b, f32x16 c) { return __builtin_amdgcn_mfma_f32_32x32x16_bf16(a, b, c, 0, 0, 0); }
; __device__ __forceinline__ f32x16 zero16() { return (f32x16){0.f, 0.f, 0.f, 0.f, 0.f, 0.f, 0.f, 0.f, 0.f, 0.f, 0.f, 0.f, 0.f, 0.f, 0.f, 0.f}; }
; __device__ __forceinline__ void r1_item(const bf16_t* __restrict__ projT, bf16_t* stloc, const float* __restrict__ cosT, const float* __restrict__ sinT, float lgf2, float lgb2, int item, int seqlen, LAS unsigned char* lds) {
;     ...
;         for (int ct = 0; ct < 4; ++ct) {
;             f32x16 acc = zero16();
; #pragma unroll
;             for (int s = 0; s < 8; ++s) { const bf16x8 bfr = *(const LAS bf16x8*)(KT + (32 * ct + c) * KT_STRIDE + 16 * s + 8 * hh); acc = mfma32(af[s], bfr, acc); }
; #pragma unroll
;             for (int rg = 0; rg < 16; ++rg) { const int dv = 32 * w + (rg & 3) + 8 * (rg >> 2) + 4 * hh; dst[dv * 128 + 32 * ct + c] = (bf16_t)(cvt_pk_bf16(acc[rg], 0.f) & 0xffffu); }
;         }
;     }
;     __syncthreads();
	v_mfma_f32_32x32x16_bf16 v[2:17], v[30:33], v[34:37], v[2:17]
	ds_read_b128 v[30:33], v51 offset:34976
	s_waitcnt lgkmcnt(0)
	v_mfma_f32_32x32x16_bf16 v[2:17], v[26:29], v[30:33], v[2:17]
	ds_read_b128 v[26:29], v51 offset:35008
	s_waitcnt lgkmcnt(0)
	v_mfma_f32_32x32x16_bf16 v[2:17], v[22:25], v[26:29], v[2:17]
	ds_read_b128 v[22:25], v51 offset:35040
	s_waitcnt lgkmcnt(0)
	v_mfma_f32_32x32x16_bf16 v[2:17], v[18:21], v[22:25], v[2:17]
	v_or_b32_e32 v18, 0x60, v50
	v_ashrrev_i32_e32 v19, 31, v18
	v_lshl_add_u64 v[18:19], v[18:19], 1, s[6:7]
	v_add_co_u32_e32 v18, vcc, s26, v18
	s_nop 1
	v_addc_co_u32_e32 v19, vcc, 0, v19, vcc
	s_nop 4
	v_cvt_pk_bf16_f32 v0, v2, s0
	v_or_b32_e32 v2, 0xe0, v50
	global_store_short v[18:19], v0, off
	v_cvt_pk_bf16_f32 v0, v3, s0
	v_ashrrev_i32_e32 v3, 31, v2
	v_lshl_add_u64 v[2:3], v[2:3], 1, s[6:7]
	v_add_co_u32_e32 v2, vcc, s26, v2
	s_nop 1
	v_addc_co_u32_e32 v3, vcc, 0, v3, vcc
	global_store_short v[2:3], v0, off
	v_or_b32_e32 v2, 0x160, v50
	v_ashrrev_i32_e32 v3, 31, v2
	v_lshl_add_u64 v[2:3], v[2:3], 1, s[6:7]
	v_add_co_u32_e32 v2, vcc, s26, v2
	v_cvt_pk_bf16_f32 v0, v4, s0
	s_nop 0
	v_addc_co_u32_e32 v3, vcc, 0, v3, vcc
	global_store_short v[2:3], v0, off
	v_or_b32_e32 v2, 0x1e0, v50
	v_ashrrev_i32_e32 v3, 31, v2
	v_lshl_add_u64 v[2:3], v[2:3], 1, s[6:7]
	v_add_co_u32_e32 v2, vcc, s26, v2
	v_cvt_pk_bf16_f32 v0, v5, s0
	s_nop 0
	v_addc_co_u32_e32 v3, vcc, 0, v3, vcc
	global_store_short v[2:3], v0, off
	v_or_b32_e32 v2, 0x460, v50
	v_ashrrev_i32_e32 v3, 31, v2
	v_lshl_add_u64 v[2:3], v[2:3], 1, s[6:7]
	v_add_co_u32_e32 v2, vcc, s26, v2
	v_cvt_pk_bf16_f32 v0, v6, s0
	s_nop 0
	v_addc_co_u32_e32 v3, vcc, 0, v3, vcc
	global_store_short v[2:3], v0, off
	v_or_b32_e32 v2, 0x4e0, v50
	v_ashrrev_i32_e32 v3, 31, v2
	v_lshl_add_u64 v[2:3], v[2:3], 1, s[6:7]
	v_add_co_u32_e32 v2, vcc, s26, v2
	v_cvt_pk_bf16_f32 v0, v7, s0
	s_nop 0
	v_addc_co_u32_e32 v3, vcc, 0, v3, vcc
	global_store_short v[2:3], v0, off
	v_or_b32_e32 v2, 0x560, v50
	v_ashrrev_i32_e32 v3, 31, v2
	v_lshl_add_u64 v[2:3], v[2:3], 1, s[6:7]
	v_add_co_u32_e32 v2, vcc, s26, v2
	v_cvt_pk_bf16_f32 v0, v8, s0
	s_nop 0
	v_addc_co_u32_e32 v3, vcc, 0, v3, vcc
	global_store_short v[2:3], v0, off
	v_or_b32_e32 v2, 0x5e0, v50
	v_ashrrev_i32_e32 v3, 31, v2
	v_lshl_add_u64 v[2:3], v[2:3], 1, s[6:7]
	v_add_co_u32_e32 v2, vcc, s26, v2
	v_cvt_pk_bf16_f32 v0, v9, s0
	s_nop 0
	v_addc_co_u32_e32 v3, vcc, 0, v3, vcc
	global_store_short v[2:3], v0, off
	v_add_co_u32_e32 v2, vcc, s26, v66
	v_cvt_pk_bf16_f32 v0, v10, s0
	s_nop 0
	v_addc_co_u32_e32 v3, vcc, 0, v67, vcc
	global_store_short v[2:3], v0, off
	v_add_co_u32_e32 v2, vcc, s26, v64
	v_cvt_pk_bf16_f32 v0, v11, s0
	s_nop 0
	v_addc_co_u32_e32 v3, vcc, 0, v65, vcc
	global_store_short v[2:3], v0, off
	v_add_co_u32_e32 v2, vcc, s26, v62
	v_cvt_pk_bf16_f32 v0, v12, s0
	s_nop 0
	v_addc_co_u32_e32 v3, vcc, 0, v63, vcc
	global_store_short v[2:3], v0, off
	v_add_co_u32_e32 v2, vcc, s26, v60
	v_cvt_pk_bf16_f32 v0, v13, s0
	s_nop 0
	v_addc_co_u32_e32 v3, vcc, 0, v61, vcc
	global_store_short v[2:3], v0, off
	v_add_co_u32_e32 v2, vcc, s26, v58
	v_cvt_pk_bf16_f32 v0, v14, s0
	s_nop 0
	v_addc_co_u32_e32 v3, vcc, 0, v59, vcc
	global_store_short v[2:3], v0, off
	v_add_co_u32_e32 v2, vcc, s26, v56
	v_cvt_pk_bf16_f32 v0, v15, s0
	s_nop 0
	v_addc_co_u32_e32 v3, vcc, 0, v57, vcc
	global_store_short v[2:3], v0, off
	v_add_co_u32_e32 v2, vcc, s26, v54
	v_cvt_pk_bf16_f32 v0, v16, s0
	s_nop 0
	v_addc_co_u32_e32 v3, vcc, 0, v55, vcc
	global_store_short v[2:3], v0, off
	v_cvt_pk_bf16_f32 v0, v17, s0
	s_add_u32 s0, s0, s54
	v_add_co_u32_e32 v2, vcc, s26, v52
	s_addc_u32 s1, s1, s55
	s_nop 0
	v_addc_co_u32_e32 v3, vcc, 0, v53, vcc
	s_cmpk_gt_i32 s42, 0x1ff
	global_store_short v[2:3], v0, off
	s_waitcnt vmcnt(63) expcnt(7) lgkmcnt(15)
	s_barrier
	s_cbranch_scc0 .LBB0_361
